# gdnpre: q0/q1 2-byte stores merged into 8-byte stores; dt_bias/a_log loads hoisted next to ga/gb loads; phase0 item-top vmcnt drain removed
# speedup vs baseline: 1.0698x; 1.0334x over previous
.LBB0_221:
	v_or_b32_e32 v38, s97, v34
	v_mov_b64_e32 v[46:47], s[34:35]
	v_mad_i64_i32 v[46:47], s[98:99], v38, s9, v[46:47]
	v_lshl_or_b32 v38, v68, 2, s11
	v_add_u32_e32 v54, 0xb00, v38
	v_add_u32_e32 v56, 0xb08, v38
	v_ashrrev_i32_e32 v55, 31, v54
	v_ashrrev_i32_e32 v57, 31, v56
	v_lshl_add_u64 v[54:55], v[54:55], 1, v[46:47]
	v_lshl_add_u64 v[46:47], v[56:57], 1, v[46:47]
	v_readlane_b32 s2, v246, 34
	s_nop 1
	v_lshl_add_u32 v168, v68, 2, s2
	v_or_b32_e32 v168, s11, v168
	v_ashrrev_i32_e32 v169, 31, v168
	v_lshl_add_u64 v[170:171], v[168:169], 2, s[68:69]
	v_lshl_add_u64 v[168:169], v[168:169], 2, s[66:67]
	global_load_dword v234, v[170:171], off
	global_load_dword v235, v[168:169], off
	global_load_ushort v38, v[54:55], off
	s_nop 0
	global_load_ushort v46, v[46:47], off
	s_waitcnt vmcnt(1)
	v_lshlrev_b32_e32 v45, 16, v38
	s_waitcnt vmcnt(0)
	v_lshlrev_b32_e32 v38, 16, v46
	s_or_b64 exec, exec, s[12:13]
	s_and_saveexec_b64 s[12:13], s[0:1]
	s_cbranch_execz .LBB0_210

.LBB0_233:
	v_readlane_b32 s2, v246, 34
	s_nop 1
	v_lshl_add_u32 v2, v68, 2, s2
	v_or_b32_e32 v2, s11, v2
	v_ashrrev_i32_e32 v3, 31, v2
	v_lshl_add_u64 v[6:7], v[2:3], 2, s[68:69]
	v_mov_b32_e32 v5, v234
	s_mov_b32 s2, 0x41a00000
	v_add_f32_e32 v5, v45, v5
	v_cmp_nlt_f32_e32 vcc, s2, v5
	s_and_saveexec_b64 s[40:41], vcc
	s_cbranch_execz .LBB0_235
	v_mul_f32_e32 v6, 0x3fb8aa3b, v5
	v_rndne_f32_e32 v7, v6
	s_mov_b32 s2, 0x3fb8aa3b
	v_sub_f32_e32 v8, v6, v7
	v_fma_f32 v6, v5, s2, -v6
	v_fmac_f32_e32 v6, 0x32a5705f, v5
	v_add_f32_e32 v6, v8, v6
	v_cvt_i32_f32_e32 v7, v7
	v_exp_f32_e32 v6, v6
	s_mov_b32 s2, 0xc2ce8ed0
	v_cmp_ngt_f32_e32 vcc, s2, v5
	s_mov_b32 s2, 0x42b17218
	v_ldexp_f32 v6, v6, v7
	v_cndmask_b32_e32 v6, 0, v6, vcc
	v_cmp_nlt_f32_e32 vcc, s2, v5
	s_mov_b32 s2, 0x3f2aaaab
	s_nop 0
	v_cndmask_b32_e32 v5, v190, v6, vcc
	v_add_f32_e32 v8, 1.0, v5
	v_add_f32_e32 v6, -1.0, v8
	v_sub_f32_e32 v7, v6, v8
	v_add_f32_e32 v7, 1.0, v7
	v_sub_f32_e32 v6, v5, v6
	v_add_f32_e32 v9, v6, v7
	v_frexp_mant_f32_e32 v10, v8
	v_cvt_f64_f32_e32 v[6:7], v8
	v_frexp_exp_i32_f64_e32 v6, v[6:7]
	v_cmp_gt_f32_e32 vcc, s2, v10
	s_mov_b32 s2, 0x3f317218
	s_nop 0
	v_subbrev_co_u32_e32 v14, vcc, 0, v6, vcc
	v_sub_u32_e32 v6, 0, v14
	v_ldexp_f32 v7, v8, v6
	v_add_f32_e32 v8, -1.0, v7
	v_add_f32_e32 v10, 1.0, v7
	v_ldexp_f32 v6, v9, v6
	v_add_f32_e32 v9, 1.0, v8
	v_add_f32_e32 v11, -1.0, v10
	v_sub_f32_e32 v9, v7, v9
	v_sub_f32_e32 v7, v7, v11
	v_add_f32_e32 v9, v6, v9
	v_add_f32_e32 v6, v6, v7
	v_add_f32_e32 v15, v10, v6
	v_rcp_f32_e32 v17, v15
	v_sub_f32_e32 v7, v10, v15
	v_add_f32_e32 v16, v6, v7
	v_add_f32_e32 v7, v8, v9
	v_mul_f32_e32 v19, v7, v17
	v_sub_f32_e32 v6, v8, v7
	v_mul_f32_e32 v8, v15, v19
	v_fma_f32 v10, v19, v15, -v8
	v_fmac_f32_e32 v10, v19, v16
	v_add_f32_e32 v18, v9, v6
	v_add_f32_e32 v6, v8, v10
	v_sub_f32_e32 v9, v7, v6
	v_pk_add_f32 v[12:13], v[6:7], v[8:9] neg_lo:[0,1] neg_hi:[0,1]
	v_mov_b32_e32 v11, v6
	v_pk_add_f32 v[6:7], v[12:13], v[10:11] neg_lo:[0,1] neg_hi:[0,1]
	s_nop 0
	v_add_f32_e32 v7, v18, v7
	v_add_f32_e32 v6, v6, v7
	v_add_f32_e32 v7, v9, v6
	v_mul_f32_e32 v18, v17, v7
	v_mul_f32_e32 v8, v15, v18
	v_fma_f32 v10, v18, v15, -v8
	v_fmac_f32_e32 v10, v18, v16
	v_sub_f32_e32 v9, v9, v7
	v_add_f32_e32 v15, v6, v9
	v_add_f32_e32 v6, v8, v10
	v_sub_f32_e32 v9, v7, v6
	v_pk_add_f32 v[12:13], v[6:7], v[8:9] neg_lo:[0,1] neg_hi:[0,1]
	v_mov_b32_e32 v11, v6
	v_pk_add_f32 v[6:7], v[12:13], v[10:11] neg_lo:[0,1] neg_hi:[0,1]
	s_nop 0
	v_add_f32_e32 v7, v15, v7
	v_add_f32_e32 v6, v6, v7
	v_add_f32_e32 v7, v19, v18
	v_add_f32_e32 v6, v9, v6
	v_sub_f32_e32 v8, v7, v19
	v_mul_f32_e32 v6, v17, v6
	v_sub_f32_e32 v8, v18, v8
	v_add_f32_e32 v8, v8, v6
	v_add_f32_e32 v10, v7, v8
	v_mul_f32_e32 v11, v10, v10
	v_fmamk_f32 v6, v11, 0x3e9b6dac, v218
	v_fmaak_f32 v151, v11, v6, 0x3f2aaada
	v_cvt_f32_i32_e32 v6, v14
	v_sub_f32_e32 v7, v10, v7
	v_sub_f32_e32 v7, v8, v7
	v_ldexp_f32 v12, v7, 1
	v_mul_f32_e32 v7, v10, v11
	v_ldexp_f32 v9, v10, 1
	v_pk_mul_f32 v[10:11], v[6:7], v[150:151]
	s_nop 0
	v_fma_f32 v8, v6, s2, -v10
	v_fmac_f32_e32 v8, 0xb102e308, v6
	v_pk_add_f32 v[6:7], v[10:11], v[8:9]
	s_mov_b32 s2, 0x7f800000
	v_sub_f32_e32 v9, v7, v9
	v_sub_f32_e32 v9, v11, v9
	v_add_f32_e32 v13, v12, v9
	v_mov_b32_e32 v12, v10
	v_pk_add_f32 v[10:11], v[6:7], v[10:11] neg_lo:[0,1] neg_hi:[0,1]
	v_pk_add_f32 v[14:15], v[6:7], v[12:13]
	v_mov_b32_e32 v9, v6
	v_mov_b32_e32 v11, v15
	v_pk_add_f32 v[16:17], v[8:9], v[10:11] neg_lo:[0,1] neg_hi:[0,1]
	v_pk_add_f32 v[8:9], v[8:9], v[10:11]
	v_mov_b32_e32 v12, v13
	v_pk_add_f32 v[10:11], v[8:9], v[6:7] op_sel:[1,0] op_sel_hi:[0,1] neg_lo:[0,1] neg_hi:[0,1]
	v_pk_add_f32 v[18:19], v[14:15], v[10:11] op_sel_hi:[1,0] neg_lo:[0,1] neg_hi:[0,1]
	v_mov_b32_e32 v14, v15
	v_mov_b32_e32 v15, v9
	v_pk_mov_b32 v[10:11], v[6:7], v[10:11] op_sel:[1,0]
	v_mov_b32_e32 v13, v6
	v_pk_add_f32 v[10:11], v[14:15], v[10:11] neg_lo:[0,1] neg_hi:[0,1]
	v_mov_b32_e32 v18, v16
	v_pk_add_f32 v[6:7], v[12:13], v[10:11] neg_lo:[0,1] neg_hi:[0,1]
	v_mov_b32_e32 v17, v9
	v_pk_add_f32 v[10:11], v[18:19], v[6:7]
	v_cmp_neq_f32_e32 vcc, s2, v5
	v_pk_add_f32 v[12:13], v[10:11], v[10:11] op_sel:[0,1] op_sel_hi:[1,0]
	s_mov_b32 s2, 0x33800000
	v_pk_add_f32 v[8:9], v[8:9], v[12:13] op_sel:[1,0] op_sel_hi:[0,1]
	v_mov_b32_e32 v11, v8
	v_pk_add_f32 v[14:15], v[10:11], v[16:17] neg_lo:[0,1] neg_hi:[0,1]
	v_mov_b32_e32 v7, v12
	v_sub_f32_e32 v9, v10, v14
	v_pk_add_f32 v[6:7], v[6:7], v[14:15] neg_lo:[0,1] neg_hi:[0,1]
	v_sub_f32_e32 v9, v16, v9
	v_add_f32_e32 v6, v6, v9
	v_add_f32_e32 v6, v6, v7
	v_add_f32_e32 v6, v8, v6
	v_cndmask_b32_e32 v6, v190, v6, vcc
	v_cmp_lt_f32_e64 vcc, |v5|, s2
	s_nop 1
	v_cndmask_b32_e32 v5, v6, v5, vcc
.LBB0_235:
	s_or_b64 exec, exec, s[40:41]
	v_lshl_add_u64 v[2:3], v[2:3], 2, s[66:67]
	v_mov_b32_e32 v2, v235
	s_mov_b32 s2, 0x3fb8aa3b
	v_mul_f32_e32 v3, 0x3fb8aa3b, v2
	v_fma_f32 v6, v2, s2, -v3
	v_rndne_f32_e32 v7, v3
	v_fmac_f32_e32 v6, 0x32a5705f, v2
	v_sub_f32_e32 v3, v3, v7
	v_add_f32_e32 v3, v3, v6
	v_exp_f32_e32 v3, v3
	v_cvt_i32_f32_e32 v6, v7
	s_mov_b32 s2, 0xc2ce8ed0
	v_cmp_ngt_f32_e32 vcc, s2, v2
	s_mov_b32 s2, 0x42b17218
	v_ldexp_f32 v3, v3, v6
	v_cndmask_b32_e32 v3, 0, v3, vcc
	v_cmp_nlt_f32_e32 vcc, s2, v2
	s_mov_b32 s2, 0xbfb8aa3b
	s_nop 0
	v_cndmask_b32_e32 v2, v190, v3, vcc
	v_mul_f32_e64 v2, v5, -v2
	v_add_u32_e32 v3, 0x11200, v4
	ds_write_b32 v3, v2
	v_mul_f32_e32 v2, 0xbfb8aa3b, v38
	v_rndne_f32_e32 v3, v2
	v_sub_f32_e32 v5, v2, v3
	v_fma_f32 v2, v38, s2, -v2
	v_fmac_f32_e32 v2, 0xb2a5705f, v38
	v_add_f32_e32 v2, v5, v2
	v_exp_f32_e32 v2, v2
	v_cvt_i32_f32_e32 v3, v3
	s_mov_b32 s2, 0x42ce8ed0
	v_cmp_nlt_f32_e32 vcc, s2, v38
	s_mov_b32 s2, 0xc2b17218
	v_ldexp_f32 v2, v2, v3
	v_cndmask_b32_e32 v2, 0, v2, vcc
	v_cmp_ngt_f32_e32 vcc, s2, v38
	s_nop 1
	v_cndmask_b32_e32 v2, v190, v2, vcc
	v_add_f32_e32 v2, 1.0, v2
	v_div_scale_f32 v3, s[12:13], v2, v2, 1.0
	v_rcp_f32_e32 v5, v3
	s_nop 0
	v_fma_f32 v6, -v3, v5, 1.0
	v_fmac_f32_e32 v5, v6, v5
	v_div_scale_f32 v6, vcc, 1.0, v2, 1.0
	v_mul_f32_e32 v7, v6, v5
	v_fma_f32 v8, -v3, v7, v6
	v_fmac_f32_e32 v7, v8, v5
	v_fma_f32 v3, -v3, v7, v6
	v_div_fmas_f32 v3, v3, v5, v7
	v_div_fixup_f32 v2, v3, v2, 1.0
	v_add_u32_e32 v3, 0x11400, v4
	ds_write_b32 v3, v2

.LBB0_241:
	s_or_b64 exec, exec, s[40:41]
	v_mul_f32_e32 v37, 0xbfb8aa3b, v28
	v_exp_f32_e32 v37, v37
	v_mul_f32_e32 v54, 0xbfb8aa3b, v29
	v_exp_f32_e32 v54, v54
	v_mul_f32_e32 v56, 0xbfb8aa3b, v27
	v_add_f32_e32 v37, 1.0, v37
	v_exp_f32_e32 v56, v56
	v_add_f32_e32 v55, 1.0, v54
	v_rcp_f32_e32 v54, v37
	v_mul_f32_e32 v37, 0xbfb8aa3b, v26
	v_rcp_f32_e32 v55, v55
	v_exp_f32_e32 v37, v37
	s_mov_b32 s0, 0x358637bd
	s_mov_b32 s2, 0x800000
	v_pk_mul_f32 v[70:71], v[28:29], v[54:55]
	v_add_f32_e32 v28, 1.0, v37
	v_add_f32_e32 v29, 1.0, v56
	v_mul_f32_e32 v37, 0xbfb8aa3b, v24
	v_mul_f32_e32 v54, 0xbfb8aa3b, v25
	v_rcp_f32_e32 v28, v28
	v_rcp_f32_e32 v29, v29
	v_exp_f32_e32 v37, v37
	v_exp_f32_e32 v54, v54
	s_waitcnt lgkmcnt(0)
	s_barrier
	v_pk_mul_f32 v[62:63], v[26:27], v[28:29]
	v_add_f32_e32 v26, 1.0, v37
	v_add_f32_e32 v27, 1.0, v54
	v_mul_f32_e32 v28, 0xbfb8aa3b, v22
	v_mul_f32_e32 v29, 0xbfb8aa3b, v23
	v_rcp_f32_e32 v26, v26
	v_rcp_f32_e32 v27, v27
	v_exp_f32_e32 v28, v28
	v_exp_f32_e32 v29, v29
	v_lshlrev_b32_e32 v37, 4, v69
	v_pk_mul_f32 v[60:61], v[24:25], v[26:27]
	v_add_f32_e32 v24, 1.0, v28
	v_add_f32_e32 v25, 1.0, v29
	v_rcp_f32_e32 v24, v24
	v_rcp_f32_e32 v25, v25
	v_mul_f32_e32 v26, 0xbfb8aa3b, v14
	v_mul_f32_e32 v27, 0xbfb8aa3b, v15
	v_exp_f32_e32 v26, v26
	v_exp_f32_e32 v27, v27
	v_pk_mul_f32 v[58:59], v[22:23], v[24:25]
	v_mul_f32_e32 v24, 0xbfb8aa3b, v16
	v_mul_f32_e32 v25, 0xbfb8aa3b, v17
	v_exp_f32_e32 v24, v24
	v_exp_f32_e32 v25, v25
	v_add_f32_e32 v22, 1.0, v26
	v_add_f32_e32 v23, 1.0, v27
	v_rcp_f32_e32 v22, v22
	v_rcp_f32_e32 v23, v23
	v_add_f32_e32 v24, 1.0, v24
	v_add_f32_e32 v25, 1.0, v25
	v_rcp_f32_e32 v24, v24
	v_rcp_f32_e32 v25, v25
	v_pk_mul_f32 v[56:57], v[14:15], v[22:23]
	s_waitcnt lgkmcnt(0)
	v_pk_add_f32 v[14:15], v[64:65], v[66:67]
	v_mul_f32_e32 v26, 0xbfb8aa3b, v18
	v_mul_f32_e32 v27, 0xbfb8aa3b, v19
	v_mul_f32_e32 v28, 0xbfb8aa3b, v20
	v_mul_f32_e32 v29, 0xbfb8aa3b, v21
	v_pk_add_f32 v[14:15], v[14:15], s[0:1] op_sel_hi:[1,0]
	v_exp_f32_e32 v26, v26
	v_exp_f32_e32 v27, v27
	v_exp_f32_e32 v28, v28
	v_exp_f32_e32 v29, v29
	v_pk_mul_f32 v[54:55], v[16:17], v[24:25]
	v_mul_f32_e32 v16, 0x4b800000, v15
	v_cmp_gt_f32_e64 s[0:1], s2, v15
	v_cmp_gt_f32_e64 s[40:41], s2, v14
	v_add_f32_e32 v26, 1.0, v26
	v_cndmask_b32_e64 v15, v15, v16, s[0:1]
	v_mul_f32_e32 v16, 0x4b800000, v14
	v_rsq_f32_e32 v15, v15
	v_cndmask_b32_e64 v14, v14, v16, s[40:41]
	v_rsq_f32_e32 v16, v14
	v_add_f32_e32 v27, 1.0, v27
	v_add_f32_e32 v28, 1.0, v28
	v_add_f32_e32 v29, 1.0, v29
	v_rcp_f32_e32 v26, v26
	v_rcp_f32_e32 v27, v27
	v_rcp_f32_e32 v28, v28
	v_rcp_f32_e32 v29, v29
	v_mul_f32_e32 v14, 0x45800000, v15
	v_cndmask_b32_e64 v14, v15, v14, s[0:1]
	v_mul_f32_e32 v15, 0x45800000, v16
	v_mul_f32_e32 v14, 0x3e000000, v14
	v_cndmask_b32_e64 v16, v16, v15, s[40:41]
	s_mul_i32 s0, s10, 0xa000
	v_pk_mul_f32 v[22:23], v[18:19], v[26:27]
	v_pk_mul_f32 v[18:19], v[20:21], v[28:29]
	v_pk_mul_f32 v[64:65], v[2:3], v[16:17] op_sel_hi:[1,0]
	v_pk_mul_f32 v[20:21], v[38:39], v[14:15] op_sel_hi:[1,0]
	v_mov_b32_e32 v38, s0
	v_lshl_add_u32 v2, v35, 2, 0
	s_add_i32 s0, 0, 0x11600
	v_pk_mul_f32 v[72:73], v[10:11], v[14:15] op_sel_hi:[1,0]
	v_add_u32_e32 v2, 0x11200, v2
	v_mov_b32_e32 v10, s0
	v_pk_mul_f32 v[4:5], v[4:5], v[14:15] op_sel_hi:[1,0]
	v_pk_mul_f32 v[66:67], v[6:7], v[14:15] op_sel_hi:[1,0]
	v_pk_mul_f32 v[76:77], v[50:51], v[14:15] op_sel_hi:[1,0]
	v_pk_mul_f32 v[78:79], v[44:45], v[16:17] op_sel_hi:[1,0]
	v_pk_mul_f32 v[50:51], v[46:47], v[14:15] op_sel_hi:[1,0]
	v_pk_mul_f32 v[44:45], v[42:43], v[14:15] op_sel_hi:[1,0]
	v_pk_mul_f32 v[30:31], v[30:31], v[14:15] op_sel_hi:[1,0]
	ds_read2st64_b32 v[2:3], v2 offset1:1
	ds_read_b64 v[14:15], v10
	v_mov_b32_e32 v39, v0
	v_lshl_add_u64 v[6:7], v[38:39], 1, s[24:25]
	v_pk_mul_f32 v[42:43], v[40:41], v[16:17] op_sel_hi:[1,0]
	s_waitcnt lgkmcnt(1)
	v_mul_f32_e32 v10, 0x3fb8aa3b, v2
	s_waitcnt lgkmcnt(0)
	v_sub_f32_e32 v2, v14, v2
	v_mul_f32_e32 v2, 0x3fb8aa3b, v2
	v_exp_f32_e32 v81, v2
	v_sub_f32_e32 v2, v15, v3
	v_mul_f32_e32 v2, 0x3fb8aa3b, v2
	v_exp_f32_e32 v82, v2
	v_lshlrev_b32_e32 v2, 6, v35
	v_exp_f32_e32 v39, v10
	v_mul_f32_e32 v10, 0x3fb8aa3b, v3
	v_ashrrev_i32_e32 v3, 31, v2
	v_lshl_add_u64 v[2:3], v[2:3], 1, v[6:7]
	s_mov_b64 s[0:1], 0x2000
	v_sub_u32_e32 v40, 63, v35
	v_lshl_add_u64 v[24:25], v[2:3], 0, s[0:1]
	v_lshlrev_b32_e32 v2, 6, v40
	v_pk_mul_f32 v[74:75], v[12:13], v[16:17] op_sel_hi:[1,0]
	v_ashrrev_i32_e32 v3, 31, v2
	v_lshlrev_b32_e32 v11, 1, v35
	v_lshrrev_b32_e32 v12, 2, v35
	v_exp_f32_e32 v80, v10
	v_lshl_add_u64 v[2:3], v[2:3], 1, v[6:7]
	s_mov_b64 s[0:1], 0xc000
	v_and_b32_e32 v10, 32, v35
	v_and_b32_e32 v11, 24, v11
	v_and_b32_e32 v12, 4, v12
	v_lshl_add_u64 v[26:27], v[2:3], 0, s[0:1]
	v_lshlrev_b32_e32 v2, 11, v69
	v_mov_b32_e32 v3, v0
	v_or3_b32 v10, v11, v10, v12
	v_lshlrev_b32_e32 v10, 1, v10
	v_mov_b32_e32 v11, v0
	v_lshl_add_u64 v[2:3], v[6:7], 0, v[2:3]
	v_lshl_add_u64 v[6:7], v[2:3], 0, v[10:11]
	v_lshrrev_b32_e32 v10, 1, v1
	v_and_b32_e32 v10, 6, v10
	v_lshl_add_u64 v[12:13], v[6:7], 0, v[10:11]
	v_lshlrev_b32_e32 v7, 1, v40
	v_lshrrev_b32_e32 v10, 2, v40
	v_and_b32_e32 v6, 32, v40
	v_and_b32_e32 v7, 24, v7
	v_and_b32_e32 v10, 4, v10
	v_or3_b32 v6, v7, v6, v10
	v_lshlrev_b32_e32 v6, 1, v6
	v_mov_b32_e32 v7, v0
	v_lshl_add_u64 v[2:3], v[2:3], 0, v[6:7]
	v_and_b32_e32 v6, 3, v40
	v_lshlrev_b32_e32 v6, 1, v6
	v_pk_mul_f32 v[46:47], v[48:49], v[16:17] op_sel_hi:[1,0]
	v_lshl_add_u64 v[48:49], v[2:3], 0, v[6:7]
	v_lshlrev_b32_e32 v3, 2, v69
	v_and_b32_e32 v2, 32, v37
	v_and_b32_e32 v6, 4, v3
	s_mov_b64 s[0:1], 0x6000
	v_or_b32_e32 v7, v2, v6
	v_pk_mul_f32 v[8:9], v[8:9], v[16:17] op_sel_hi:[1,0]
	v_pk_mul_f32 v[28:29], v[32:33], v[16:17] op_sel_hi:[1,0]
	v_pk_mul_f32 v[16:17], v[52:53], v[16:17] op_sel_hi:[1,0]
	v_lshl_add_u64 v[32:33], v[12:13], 0, s[0:1]
	s_mov_b64 s[0:1], 0x10000
	v_or_b32_e32 v83, v2, v3
	v_mul_f32_e32 v3, v4, v39
	v_lshlrev_b32_e32 v52, 1, v7
	v_mov_b32_e32 v53, v0
	v_or_b32_e32 v37, v6, v37
	v_cvt_pk_bf16_f32 v6, v70, v71
	v_cvt_pk_bf16_f32 v3, v3, s0
	v_lshl_add_u64 v[70:71], v[24:25], 0, v[52:53]
	v_and_b32_e32 v152, 0xffff, v3
	v_mul_f32_e32 v3, v4, v80
	v_cvt_pk_bf16_f32 v3, v3, s0
	v_lshl_add_u64 v[52:53], v[26:27], 0, v[52:53]
	v_and_b32_e32 v154, 0xffff, v3
	v_mul_f32_e32 v3, v64, v81
	v_lshl_add_u64 v[40:41], v[48:49], 0, s[0:1]
	v_cvt_pk_bf16_f32 v3, v3, s0
	v_add_co_u32_e64 v12, s[0:1], s19, v12
	v_cvt_pk_bf16_f32 v10, v4, v5
	s_nop 0
	v_addc_co_u32_e64 v13, s[0:1], 0, v13, s[0:1]
	global_store_short v[12:13], v3, off
	v_mul_f32_e32 v3, v64, v82
	v_cvt_pk_bf16_f32 v3, v3, s0
	s_mov_b32 s0, 0x10000
	v_add_co_u32_e64 v12, s[0:1], s0, v48
	v_mul_f32_e32 v4, v66, v39
	s_nop 0
	v_addc_co_u32_e64 v13, s[0:1], 0, v49, s[0:1]
	global_store_short v[12:13], v3, off
	v_mul_f32_e32 v3, v5, v39
	v_cvt_pk_bf16_f32 v3, v3, s0
	v_lshl_or_b32 v152, v3, 16, v152
	v_mul_f32_e32 v3, v5, v80
	v_cvt_pk_bf16_f32 v3, v3, s0
	v_lshl_or_b32 v154, v3, 16, v154
	v_mul_f32_e32 v3, v65, v81
	v_cvt_pk_bf16_f32 v3, v3, s0
	global_store_short v[32:33], v3, off offset:128
	v_mul_f32_e32 v3, v65, v82
	v_cvt_pk_bf16_f32 v3, v3, s0
	v_cvt_pk_bf16_f32 v4, v4, s0
	global_store_short v[40:41], v3, off offset:128
	v_and_b32_e32 v153, 0xffff, v4
	v_mul_f32_e32 v4, v66, v80
	v_cvt_pk_bf16_f32 v4, v4, s0
	v_and_b32_e32 v155, 0xffff, v4
	v_mul_f32_e32 v4, v8, v81
	v_cvt_pk_bf16_f32 v4, v4, s0
	global_store_short v[32:33], v4, off offset:256
	v_mul_f32_e32 v4, v8, v82
	v_cvt_pk_bf16_f32 v4, v4, s0
	global_store_short v[40:41], v4, off offset:256
	v_mul_f32_e32 v4, v67, v39
	v_cvt_pk_bf16_f32 v4, v4, s0
	v_lshl_or_b32 v153, v4, 16, v153
	global_store_dwordx2 v[70:71], v[152:153], off
	v_mul_f32_e32 v4, v67, v80
	v_cvt_pk_bf16_f32 v4, v4, s0
	v_lshl_or_b32 v155, v4, 16, v155
	global_store_dwordx2 v[52:53], v[154:155], off
	v_mul_f32_e32 v4, v9, v81
	v_cvt_pk_bf16_f32 v3, v8, v9
	v_cvt_pk_bf16_f32 v4, v4, s0
	v_cvt_pk_bf16_f32 v8, v60, v61
	v_lshlrev_b32_e32 v60, 1, v83
	global_store_short v[32:33], v4, off offset:384
	v_mul_f32_e32 v4, v9, v82
	v_mul_f32_e32 v5, v72, v39
	v_or_b32_e32 v48, 16, v60
	v_mov_b32_e32 v49, v0
	v_cvt_pk_bf16_f32 v4, v4, s0
	v_cvt_pk_bf16_f32 v5, v5, s0
	v_lshl_add_u64 v[52:53], v[24:25], 0, v[48:49]
	global_store_short v[40:41], v4, off offset:384
	v_and_b32_e32 v156, 0xffff, v5
	v_mul_f32_e32 v5, v72, v80
	v_cvt_pk_bf16_f32 v5, v5, s0
	v_lshl_add_u64 v[48:49], v[26:27], 0, v[48:49]
	v_and_b32_e32 v158, 0xffff, v5
	v_mul_f32_e32 v5, v74, v81
	v_cvt_pk_bf16_f32 v5, v5, s0
	global_store_short v[32:33], v5, off offset:512
	v_mul_f32_e32 v5, v74, v82
	v_cvt_pk_bf16_f32 v5, v5, s0
	global_store_short v[40:41], v5, off offset:512
	v_mul_f32_e32 v5, v73, v39
	v_or_b32_e32 v48, 18, v60
	v_mov_b32_e32 v49, v0
	v_cvt_pk_bf16_f32 v5, v5, s0
	v_lshl_add_u64 v[52:53], v[24:25], 0, v[48:49]
	v_lshl_or_b32 v156, v5, 16, v156
	v_mul_f32_e32 v5, v73, v80
	v_cvt_pk_bf16_f32 v5, v5, s0
	v_lshl_add_u64 v[48:49], v[26:27], 0, v[48:49]
	v_lshl_or_b32 v158, v5, 16, v158
	v_mul_f32_e32 v5, v75, v81
	v_cvt_pk_bf16_f32 v5, v5, s0
	v_mul_f32_e32 v48, v76, v39
	global_store_short v[32:33], v5, off offset:640
	v_mul_f32_e32 v5, v75, v82
	v_cvt_pk_bf16_f32 v9, v58, v59
	v_cvt_pk_bf16_f32 v58, v48, s0
	v_or_b32_e32 v48, 20, v60
	v_mov_b32_e32 v49, v0
	v_cvt_pk_bf16_f32 v5, v5, s0
	v_lshl_add_u64 v[52:53], v[24:25], 0, v[48:49]
	global_store_short v[40:41], v5, off offset:640
	v_and_b32_e32 v157, 0xffff, v58
	v_mul_f32_e32 v52, v76, v80
	v_cvt_pk_bf16_f32 v52, v52, s0
	v_lshl_add_u64 v[48:49], v[26:27], 0, v[48:49]
	v_and_b32_e32 v159, 0xffff, v52
	v_mul_f32_e32 v48, v78, v81
	v_cvt_pk_bf16_f32 v48, v48, s0
	global_store_short v[32:33], v48, off offset:768
	v_mul_f32_e32 v48, v78, v82
	v_cvt_pk_bf16_f32 v48, v48, s0
	global_store_short v[40:41], v48, off offset:768
	v_mul_f32_e32 v48, v77, v39
	v_cvt_pk_bf16_f32 v58, v48, s0
	v_or_b32_e32 v48, 22, v60
	v_mov_b32_e32 v49, v0
	v_lshl_add_u64 v[52:53], v[24:25], 0, v[48:49]
	v_lshl_or_b32 v157, v58, 16, v157
	global_store_dwordx2 v[52:53], v[156:157], off offset:-6
	v_mul_f32_e32 v52, v77, v80
	v_cvt_pk_bf16_f32 v52, v52, s0
	v_lshl_add_u64 v[48:49], v[26:27], 0, v[48:49]
	v_lshl_or_b32 v159, v52, 16, v159
	global_store_dwordx2 v[48:49], v[158:159], off offset:-6
	v_mul_f32_e32 v48, v79, v81
	v_cvt_pk_bf16_f32 v48, v48, s0
	v_lshlrev_b32_e32 v37, 1, v37
	global_store_short v[32:33], v48, off offset:896
	v_mul_f32_e32 v48, v79, v82
	v_mul_f32_e32 v49, v50, v39
	v_or_b32_e32 v58, 32, v37
	v_mov_b32_e32 v59, v0
	v_cvt_pk_bf16_f32 v48, v48, s0
	v_cvt_pk_bf16_f32 v49, v49, s0
	v_lshl_add_u64 v[60:61], v[24:25], 0, v[58:59]
	global_store_short v[40:41], v48, off offset:896
	v_and_b32_e32 v160, 0xffff, v49
	v_mul_f32_e32 v49, v50, v80
	v_cvt_pk_bf16_f32 v49, v49, s0
	v_lshl_add_u64 v[58:59], v[26:27], 0, v[58:59]
	v_cvt_pk_bf16_f32 v48, v46, v47
	v_and_b32_e32 v162, 0xffff, v49
	v_mul_f32_e32 v49, v46, v81
	v_mul_f32_e32 v46, v46, v82
	v_cvt_pk_bf16_f32 v46, v46, s0
	global_store_short v[40:41], v46, off offset:1024
	v_mul_f32_e32 v46, v51, v39
	v_or_b32_e32 v58, 34, v37
	v_mov_b32_e32 v59, v0
	v_cvt_pk_bf16_f32 v49, v49, s0
	v_cvt_pk_bf16_f32 v46, v46, s0
	v_lshl_add_u64 v[60:61], v[24:25], 0, v[58:59]
	global_store_short v[32:33], v49, off offset:1024
	v_lshl_or_b32 v160, v46, 16, v160
	v_mul_f32_e32 v46, v51, v80
	v_cvt_pk_bf16_f32 v52, v50, v51
	v_cvt_pk_bf16_f32 v46, v46, s0
	v_lshl_add_u64 v[50:51], v[26:27], 0, v[58:59]
	v_lshl_or_b32 v162, v46, 16, v162
	v_mul_f32_e32 v46, v47, v81
	v_cvt_pk_bf16_f32 v46, v46, s0
	global_store_short v[32:33], v46, off offset:1152
	v_mul_f32_e32 v46, v47, v82
	v_cvt_pk_bf16_f32 v46, v46, s0
	global_store_short v[40:41], v46, off offset:1152
	v_mul_f32_e32 v46, v44, v39
	v_cvt_pk_bf16_f32 v56, v56, v57
	v_cvt_pk_bf16_f32 v53, v44, v45
	v_cvt_pk_bf16_f32 v57, v54, v55
	v_cvt_pk_bf16_f32 v54, v46, s0
	v_or_b32_e32 v46, 36, v37
	v_mov_b32_e32 v47, v0
	v_mul_f32_e32 v44, v44, v80
	v_lshl_add_u64 v[50:51], v[24:25], 0, v[46:47]
	v_cvt_pk_bf16_f32 v44, v44, s0
	v_lshl_add_u64 v[46:47], v[26:27], 0, v[46:47]
	v_cvt_pk_bf16_f32 v49, v42, v43
	v_and_b32_e32 v161, 0xffff, v54
	v_and_b32_e32 v163, 0xffff, v44
	v_mul_f32_e32 v44, v42, v81
	v_mul_f32_e32 v42, v42, v82
	v_cvt_pk_bf16_f32 v42, v42, s0
	v_cvt_pk_bf16_f32 v44, v44, s0
	global_store_short v[40:41], v42, off offset:1280
	v_mul_f32_e32 v42, v45, v39
	v_or_b32_e32 v46, 38, v37
	v_mov_b32_e32 v47, v0
	v_mul_f32_e32 v37, v45, v80
	global_store_short v[32:33], v44, off offset:1280
	v_cvt_pk_bf16_f32 v42, v42, s0
	v_lshl_add_u64 v[50:51], v[24:25], 0, v[46:47]
	v_cvt_pk_bf16_f32 v37, v37, s0
	v_lshl_add_u64 v[44:45], v[26:27], 0, v[46:47]
	v_lshl_or_b32 v161, v42, 16, v161
	global_store_dwordx2 v[50:51], v[160:161], off offset:-6
	v_lshl_or_b32 v163, v37, 16, v163
	global_store_dwordx2 v[44:45], v[162:163], off offset:-6
	v_mul_f32_e32 v37, v43, v81
	v_cvt_pk_bf16_f32 v37, v37, s0
	v_mul_u32_u24_e32 v2, 20, v69
	global_store_short v[32:33], v37, off offset:1408
	v_mul_f32_e32 v37, v43, v82
	v_lshlrev_b32_e32 v84, 1, v2
	v_cvt_pk_bf16_f32 v37, v37, s0
	v_cvt_pk_bf16_f32 v58, v22, v23
	v_mul_f32_e32 v22, v30, v39
	global_store_short v[40:41], v37, off offset:1408
	v_cvt_pk_bf16_f32 v54, v30, v31
	v_cvt_pk_bf16_f32 v37, v22, s0
	v_or_b32_e32 v22, 48, v84
	v_mov_b32_e32 v23, v0
	v_mul_f32_e32 v30, v30, v80
	v_lshl_add_u64 v[42:43], v[24:25], 0, v[22:23]
	v_cvt_pk_bf16_f32 v30, v30, s0
	v_lshl_add_u64 v[22:23], v[26:27], 0, v[22:23]
	v_and_b32_e32 v164, 0xffff, v37
	v_and_b32_e32 v166, 0xffff, v30
	v_mul_f32_e32 v22, v28, v81
	v_cvt_pk_bf16_f32 v22, v22, s0
	global_store_short v[32:33], v22, off offset:1536
	v_mul_f32_e32 v22, v28, v82
	v_cvt_pk_bf16_f32 v22, v22, s0
	global_store_short v[40:41], v22, off offset:1536
	v_mul_f32_e32 v22, v31, v39
	v_cvt_pk_bf16_f32 v50, v28, v29
	v_cvt_pk_bf16_f32 v28, v22, s0
	v_or_b32_e32 v22, 50, v84
	v_mov_b32_e32 v23, v0
	v_lshl_add_u64 v[42:43], v[24:25], 0, v[22:23]
	v_lshl_or_b32 v164, v28, 16, v164
	v_mul_f32_e32 v28, v31, v80
	v_cvt_pk_bf16_f32 v28, v28, s0
	v_lshl_add_u64 v[22:23], v[26:27], 0, v[22:23]
	v_lshl_or_b32 v166, v28, 16, v166
	v_mul_f32_e32 v22, v29, v81
	v_cvt_pk_bf16_f32 v22, v22, s0
	global_store_short v[32:33], v22, off offset:1664
	v_mul_f32_e32 v22, v29, v82
	v_cvt_pk_bf16_f32 v59, v18, v19
	v_mul_f32_e32 v18, v20, v39
	v_cvt_pk_bf16_f32 v22, v22, s0
	v_cvt_pk_bf16_f32 v55, v20, v21
	v_cvt_pk_bf16_f32 v28, v18, s0
	v_or_b32_e32 v18, 52, v84
	v_mov_b32_e32 v19, v0
	v_mul_f32_e32 v20, v20, v80
	global_store_short v[40:41], v22, off offset:1664
	v_lshl_add_u64 v[22:23], v[24:25], 0, v[18:19]
	v_cvt_pk_bf16_f32 v20, v20, s0
	v_lshl_add_u64 v[18:19], v[26:27], 0, v[18:19]
	v_cvt_pk_bf16_f32 v51, v16, v17
	v_and_b32_e32 v165, 0xffff, v28
	v_and_b32_e32 v167, 0xffff, v20
	v_mul_f32_e32 v18, v16, v81
	v_mul_f32_e32 v16, v16, v82
	v_cvt_pk_bf16_f32 v18, v18, s0
	v_cvt_pk_bf16_f32 v16, v16, s0
	global_store_short v[32:33], v18, off offset:1792
	global_store_short v[40:41], v16, off offset:1792
	v_mul_f32_e32 v16, v21, v39
	v_or_b32_e32 v18, 54, v84
	v_mov_b32_e32 v19, v0
	v_cvt_pk_bf16_f32 v16, v16, s0
	v_lshl_add_u64 v[22:23], v[24:25], 0, v[18:19]
	v_lshl_or_b32 v165, v16, 16, v165
	global_store_dwordx2 v[22:23], v[164:165], off offset:-6
	v_mul_f32_e32 v16, v21, v80
	v_cvt_pk_bf16_f32 v16, v16, s0
	v_lshl_add_u64 v[18:19], v[26:27], 0, v[18:19]
	v_lshl_or_b32 v167, v16, 16, v167
	global_store_dwordx2 v[18:19], v[166:167], off offset:-6
	v_mul_f32_e32 v16, v17, v81
	v_cvt_pk_bf16_f32 v16, v16, s0
	global_store_short v[32:33], v16, off offset:1920
	v_mul_f32_e32 v16, v17, v82
	v_cvt_pk_bf16_f32 v16, v16, s0
	global_store_short v[40:41], v16, off offset:1920
	v_mul_lo_u32 v16, v35, s39
	v_lshlrev_b32_e32 v17, 5, v69
	s_mov_b32 s98, 0x800000
	v_cvt_pk_bf16_f32 v2, v64, v65
	v_cvt_pk_bf16_f32 v4, v74, v75
	v_cvt_pk_bf16_f32 v5, v78, v79
	v_add3_u32 v16, 0, v16, v17
	v_cmp_eq_u32_e64 s[0:1], 0, v1
	v_cvt_pk_bf16_f32 v11, v66, v67
	v_cvt_pk_bf16_f32 v7, v62, v63
	v_cvt_pk_bf16_f32 v12, v72, v73
	v_cvt_pk_bf16_f32 v13, v76, v77
	ds_write_b128 v16, v[2:5] offset:33280
	ds_write_b128 v16, v[10:13] offset:42496
	ds_write_b128 v16, v[6:9] offset:51712
	ds_write_b128 v16, v[2:5] offset:60928
	ds_write_b128 v16, v[48:51] offset:33296
	ds_write_b128 v16, v[52:55] offset:42512
	ds_write_b128 v16, v[56:59] offset:51728
	ds_write_b128 v16, v[48:51] offset:60944
	s_and_saveexec_b64 s[12:13], s[0:1]
	s_cbranch_execz .LBB0_243
	s_lshl_b32 s0, s10, 1
	s_ashr_i32 s1, s0, 31
	s_lshl_b64 s[0:1], s[0:1], 2
	v_readlane_b32 s40, v248, 21
	v_readlane_b32 s41, v248, 22
	s_add_u32 s0, s40, s0
	s_addc_u32 s1, s41, s1
	global_store_dwordx2 v0, v[14:15], s[0:1]

.LBB0_354:
	s_cmpk_gt_i32 s48, 0xbf
	s_mov_b64 s[0:1], -1
	s_waitcnt lgkmcnt(0)
	s_barrier
	s_cbranch_scc0 .LBB0_393
	s_cmpk_gt_u32 s48, 0x8ff
	s_cbranch_scc0 .LBB0_370
	s_cmpk_lg_i32 s48, 0x920
	s_cbranch_scc0 .LBB0_358
	v_readlane_b32 s52, v246, 5
	v_lshl_add_u32 v2, s48, 12, v192
	v_mov_b32_e32 v3, v0
	v_readlane_b32 s64, v246, 17
	v_readlane_b32 s65, v246, 18
	v_or_b32_e32 v6, 0x400, v2
	v_mov_b32_e32 v7, v0
	v_lshl_add_u64 v[4:5], v[2:3], 2, s[64:65]
	v_add_u32_e32 v10, 0x500, v2
	v_mov_b32_e32 v11, v0
	v_add_u32_e32 v14, 0x600, v2
	v_mov_b32_e32 v15, v0
	v_add_u32_e32 v18, 0x700, v2
	v_mov_b32_e32 v19, v0
	v_lshl_add_u64 v[8:9], v[6:7], 2, s[64:65]
	v_lshl_add_u64 v[12:13], v[10:11], 2, s[64:65]
	v_lshl_add_u64 v[16:17], v[14:15], 2, s[64:65]
	v_lshl_add_u64 v[20:21], v[18:19], 2, s[64:65]
	global_load_dword v1, v[4:5], off
	global_load_dword v36, v[4:5], off offset:1024
	global_load_dword v37, v[4:5], off offset:2048
	global_load_dword v38, v[4:5], off offset:3072
	global_load_dword v39, v[8:9], off
	global_load_dword v40, v[12:13], off
	global_load_dword v41, v[16:17], off
	global_load_dword v42, v[20:21], off
	v_or_b32_e32 v4, 0x800, v2
	v_mov_b32_e32 v5, v0
	v_lshl_add_u64 v[8:9], v[4:5], 2, s[64:65]
	global_load_dword v43, v[8:9], off
	v_add_u32_e32 v8, 0x900, v2
	v_mov_b32_e32 v9, v0
	v_lshl_add_u64 v[12:13], v[8:9], 2, s[64:65]
	v_add_u32_e32 v16, 0xa00, v2
	v_mov_b32_e32 v17, v0
	v_add_u32_e32 v22, 0xb00, v2
	v_mov_b32_e32 v23, v0
	v_lshl_add_u64 v[20:21], v[16:17], 2, s[64:65]
	v_lshl_add_u64 v[24:25], v[22:23], 2, s[64:65]
	global_load_dword v44, v[12:13], off
	global_load_dword v45, v[20:21], off
	global_load_dword v46, v[24:25], off
	v_or_b32_e32 v12, 0xc00, v2
	v_mov_b32_e32 v13, v0
	v_lshl_add_u64 v[20:21], v[12:13], 2, s[64:65]
	v_add_u32_e32 v24, 0xd00, v2
	v_mov_b32_e32 v25, v0
	v_lshl_add_u64 v[26:27], v[24:25], 2, s[64:65]
	global_load_dword v47, v[20:21], off
	global_load_dword v48, v[26:27], off
	v_add_u32_e32 v20, 0xe00, v2
	v_mov_b32_e32 v21, v0
	v_lshl_add_u64 v[26:27], v[20:21], 2, s[64:65]
	global_load_dword v49, v[26:27], off
	v_add_u32_e32 v26, 0xf00, v2
	v_mov_b32_e32 v27, v0
	v_lshl_add_u64 v[28:29], v[26:27], 2, s[64:65]
	global_load_dword v50, v[28:29], off
	v_readlane_b32 s0, v248, 7
	v_mov_b32_e32 v29, v0
	v_readlane_b32 s1, v248, 8
	v_add_u32_e32 v28, 0x100, v2
	v_mov_b32_e32 v31, v0
	v_mov_b32_e32 v33, v0
	v_lshl_add_u64 v[34:35], v[2:3], 1, s[0:1]
	v_add_u32_e32 v30, 0x200, v2
	v_add_u32_e32 v32, 0x300, v2
	v_lshl_add_u64 v[2:3], v[28:29], 1, s[0:1]
	v_lshl_add_u64 v[28:29], v[30:31], 1, s[0:1]
	v_lshl_add_u64 v[30:31], v[32:33], 1, s[0:1]
	v_lshl_add_u64 v[6:7], v[6:7], 1, s[0:1]
	v_lshl_add_u64 v[10:11], v[10:11], 1, s[0:1]
	v_lshl_add_u64 v[14:15], v[14:15], 1, s[0:1]
	v_lshl_add_u64 v[18:19], v[18:19], 1, s[0:1]
	v_readlane_b32 s66, v246, 19
	v_readlane_b32 s67, v246, 20
	v_readlane_b32 s64, v247, 53
	v_readlane_b32 s72, v247, 61
	v_readlane_b32 s53, v246, 6
	v_readlane_b32 s54, v246, 7
	v_readlane_b32 s55, v246, 8
	v_readlane_b32 s56, v246, 9
	v_readlane_b32 s57, v246, 10
	v_readlane_b32 s58, v246, 11
	v_readlane_b32 s59, v246, 12
	v_readlane_b32 s60, v246, 13
	v_readlane_b32 s61, v246, 14
	v_readlane_b32 s62, v246, 15
	v_readlane_b32 s63, v246, 16
	v_readlane_b32 s65, v247, 54
	v_readlane_b32 s66, v247, 55
	v_readlane_b32 s67, v247, 56
	v_readlane_b32 s68, v247, 57
	v_readlane_b32 s69, v247, 58
	v_readlane_b32 s70, v247, 59
	v_readlane_b32 s71, v247, 60
	v_readlane_b32 s73, v247, 62
	v_readlane_b32 s74, v247, 63
	v_readlane_b32 s75, v246, 0
	v_readlane_b32 s76, v246, 1
	v_readlane_b32 s77, v246, 2
	s_waitcnt vmcnt(15)
	v_cvt_pk_bf16_f32 v1, v1, s0
	s_waitcnt vmcnt(14)
	v_cvt_pk_bf16_f32 v32, v36, s0
	s_waitcnt vmcnt(13)
	v_cvt_pk_bf16_f32 v33, v37, s0
	s_waitcnt vmcnt(12)
	v_cvt_pk_bf16_f32 v36, v38, s0
	global_store_short v[34:35], v1, off
	global_store_short v[2:3], v32, off
	global_store_short v[28:29], v33, off
	global_store_short v[30:31], v36, off
	s_waitcnt vmcnt(15)
	v_cvt_pk_bf16_f32 v1, v39, s0
	s_waitcnt vmcnt(14)
	v_cvt_pk_bf16_f32 v2, v40, s0
	s_waitcnt vmcnt(13)
	v_cvt_pk_bf16_f32 v3, v41, s0
	s_waitcnt vmcnt(12)
	v_cvt_pk_bf16_f32 v28, v42, s0
	global_store_short v[6:7], v1, off
	global_store_short v[10:11], v2, off
	global_store_short v[14:15], v3, off
	global_store_short v[18:19], v28, off
	v_lshl_add_u64 v[2:3], v[4:5], 1, s[0:1]
	s_waitcnt vmcnt(15)
	v_cvt_pk_bf16_f32 v1, v43, s0
	global_store_short v[2:3], v1, off
	v_lshl_add_u64 v[2:3], v[8:9], 1, s[0:1]
	v_readlane_b32 s78, v246, 3
	v_readlane_b32 s79, v246, 4
	v_readlane_b32 s72, v246, 60
	s_waitcnt vmcnt(15)
	v_cvt_pk_bf16_f32 v1, v44, s0
	global_store_short v[2:3], v1, off
	s_waitcnt vmcnt(15)
	v_cvt_pk_bf16_f32 v1, v45, s0
	v_lshl_add_u64 v[2:3], v[16:17], 1, s[0:1]
	global_store_short v[2:3], v1, off
	s_waitcnt vmcnt(15)
	v_cvt_pk_bf16_f32 v1, v46, s0
	v_lshl_add_u64 v[2:3], v[22:23], 1, s[0:1]
	global_store_short v[2:3], v1, off
	s_waitcnt vmcnt(15)
	v_cvt_pk_bf16_f32 v1, v47, s0
	v_lshl_add_u64 v[2:3], v[12:13], 1, s[0:1]
	global_store_short v[2:3], v1, off
	s_waitcnt vmcnt(15)
	v_cvt_pk_bf16_f32 v1, v48, s0
	v_lshl_add_u64 v[2:3], v[24:25], 1, s[0:1]
	global_store_short v[2:3], v1, off
	s_waitcnt vmcnt(15)
	v_cvt_pk_bf16_f32 v1, v49, s0
	v_lshl_add_u64 v[2:3], v[20:21], 1, s[0:1]
	global_store_short v[2:3], v1, off
	s_waitcnt vmcnt(15)
	v_cvt_pk_bf16_f32 v1, v50, s0
	v_lshl_add_u64 v[2:3], v[26:27], 1, s[0:1]
	global_store_short v[2:3], v1, off
	s_mov_b64 s[0:1], 0
